# v22 + nt hint on the retention gate (Gt) stores of the in-projection epilogue
# baseline (speedup 1.0000x reference)
.LBB0_187:
	s_and_b64 vcc, exec, s[6:7]
	s_cbranch_vccz .LBB0_189
	v_ashrrev_i32_e32 v167, 31, v166
	v_lshl_add_u32 v128, s14, 8, v183
	v_mov_b32_e32 v129, v145
	v_lshlrev_b64 v[130:131], 12, v[166:167]
	v_lshl_add_u64 v[130:131], s[72:73], 0, v[130:131]
	v_lshlrev_b64 v[128:129], 1, v[128:129]
	v_lshl_add_u64 v[130:131], v[130:131], 0, v[128:129]
	s_mov_b64 s[6:7], 0x80000
	v_cvt_pk_bf16_f32 v68, v68, v69
	v_cvt_pk_bf16_f32 v69, v70, v71
	v_cvt_pk_bf16_f32 v70, v64, v65
	v_lshl_add_u64 v[64:65], v[130:131], 0, s[6:7]
	s_mov_b32 s6, 0x80000
	v_cvt_pk_bf16_f32 v60, v60, v61
	v_cvt_pk_bf16_f32 v61, v62, v63
	v_cvt_pk_bf16_f32 v62, v56, v57
	v_add_co_u32_e32 v56, vcc, s6, v130
	v_cvt_pk_bf16_f32 v44, v44, v45
	v_cvt_pk_bf16_f32 v45, v46, v47
	v_cvt_pk_bf16_f32 v46, v40, v41
	v_cvt_pk_bf16_f32 v47, v42, v43
	s_mov_b64 s[6:7], 0x90000
	v_cvt_pk_bf16_f32 v108, v108, v109
	v_cvt_pk_bf16_f32 v109, v110, v111
	v_cvt_pk_bf16_f32 v110, v104, v105
	v_or_b32_e32 v104, 16, v166
	v_addc_co_u32_e32 v57, vcc, 0, v131, vcc
	global_store_dwordx4 v[64:65], v[44:47], off offset:256 nt
	v_ashrrev_i32_e32 v105, 31, v104
	v_cvt_pk_bf16_f32 v92, v92, v93
	v_lshl_add_u64 v[44:45], v[130:131], 0, s[6:7]
	s_mov_b32 s6, 0x90000
	v_cvt_pk_bf16_f32 v93, v94, v95
	v_cvt_pk_bf16_f32 v94, v88, v89
	v_or_b32_e32 v88, 32, v166
	v_add_co_u32_e32 v46, vcc, s6, v130
	v_cvt_pk_bf16_f32 v28, v28, v29
	v_cvt_pk_bf16_f32 v29, v30, v31
	v_cvt_pk_bf16_f32 v30, v24, v25
	v_cvt_pk_bf16_f32 v31, v26, v27
	s_mov_b64 s[6:7], 0xa0000
	v_lshlrev_b64 v[104:105], 12, v[104:105]
	v_ashrrev_i32_e32 v89, 31, v88
	v_cvt_pk_bf16_f32 v76, v76, v77
	v_cvt_pk_bf16_f32 v77, v78, v79
	v_cvt_pk_bf16_f32 v78, v72, v73
	v_or_b32_e32 v72, 48, v166
	v_addc_co_u32_e32 v47, vcc, 0, v131, vcc
	global_store_dwordx4 v[44:45], v[28:31], off offset:256 nt
	v_cvt_pk_bf16_f32 v111, v106, v107
	v_lshl_add_u64 v[104:105], s[72:73], 0, v[104:105]
	v_lshl_add_u64 v[28:29], v[130:131], 0, s[6:7]
	s_mov_b32 s6, 0xa0000
	v_lshlrev_b64 v[88:89], 12, v[88:89]
	v_ashrrev_i32_e32 v73, 31, v72
	v_add_co_u32_e32 v30, vcc, s6, v130
	global_store_dwordx4 v[130:131], v[108:111], off offset:256 nt
	v_cvt_pk_bf16_f32 v95, v90, v91
	v_lshl_add_u64 v[88:89], s[72:73], 0, v[88:89]
	v_lshl_add_u64 v[108:109], v[104:105], 0, v[128:129]
	v_lshlrev_b64 v[72:73], 12, v[72:73]
	v_addc_co_u32_e32 v31, vcc, 0, v131, vcc
	v_cvt_pk_bf16_f32 v12, v12, v13
	v_cvt_pk_bf16_f32 v13, v14, v15
	v_cvt_pk_bf16_f32 v14, v8, v9
	v_cvt_pk_bf16_f32 v15, v10, v11
	v_cvt_pk_bf16_f32 v124, v124, v125
	v_cvt_pk_bf16_f32 v125, v126, v127
	v_cvt_pk_bf16_f32 v126, v120, v121
	v_cvt_pk_bf16_f32 v127, v122, v123
	global_store_dwordx4 v[108:109], v[92:95], off offset:256 nt
	v_cvt_pk_bf16_f32 v79, v74, v75
	v_lshl_add_u64 v[72:73], s[72:73], 0, v[72:73]
	v_lshl_add_u64 v[92:93], v[88:89], 0, v[128:129]
	global_store_dwordx4 v[28:29], v[12:15], off offset:256 nt
	s_mov_b64 s[6:7], 0xb0000
	global_store_dwordx4 v[130:131], v[124:127], off nt
	v_add_co_u32_e32 v12, vcc, 0xb0000, v130
	global_store_dwordx4 v[92:93], v[76:79], off offset:256 nt
	v_lshl_add_u64 v[136:137], v[130:131], 0, s[6:7]
	v_addc_co_u32_e32 v13, vcc, 0, v131, vcc
	v_lshl_add_u64 v[76:77], v[72:73], 0, v[128:129]
	v_mov_b64_e32 v[134:135], v[6:7]
	v_mov_b64_e32 v[130:131], v[2:3]
	v_cvt_pk_bf16_f32 v104, v116, v117
	v_cvt_pk_bf16_f32 v105, v118, v119
	v_cvt_pk_bf16_f32 v106, v112, v113
	v_cvt_pk_bf16_f32 v107, v114, v115
	v_cvt_pk_bf16_f32 v88, v100, v101
	v_cvt_pk_bf16_f32 v89, v102, v103
	v_cvt_pk_bf16_f32 v90, v96, v97
	v_cvt_pk_bf16_f32 v91, v98, v99
	v_cvt_pk_bf16_f32 v72, v84, v85
	v_cvt_pk_bf16_f32 v73, v86, v87
	v_cvt_pk_bf16_f32 v74, v80, v81
	v_cvt_pk_bf16_f32 v75, v82, v83
	v_cvt_pk_bf16_f32 v71, v66, v67
	v_cvt_pk_bf16_f32 v63, v58, v59
	v_cvt_pk_bf16_f32 v40, v52, v53
	v_cvt_pk_bf16_f32 v41, v54, v55
	v_cvt_pk_bf16_f32 v42, v48, v49
	v_cvt_pk_bf16_f32 v43, v50, v51
	v_cvt_pk_bf16_f32 v24, v36, v37
	v_cvt_pk_bf16_f32 v25, v38, v39
	v_cvt_pk_bf16_f32 v26, v32, v33
	v_cvt_pk_bf16_f32 v27, v34, v35
	v_cvt_pk_bf16_f32 v8, v20, v21
	v_cvt_pk_bf16_f32 v9, v22, v23
	v_cvt_pk_bf16_f32 v10, v16, v17
	v_cvt_pk_bf16_f32 v11, v18, v19
	v_mov_b64_e32 v[132:133], v[4:5]
	v_mov_b64_e32 v[128:129], v[0:1]
	global_store_dwordx4 v[108:109], v[104:107], off nt
	global_store_dwordx4 v[92:93], v[88:91], off nt
	global_store_dwordx4 v[76:77], v[72:75], off nt
	global_store_dwordx4 v[76:77], v[68:71], off offset:256 nt
	global_store_dwordx4 v[56:57], v[60:63], off nt
	global_store_dwordx4 v[46:47], v[40:43], off nt
	global_store_dwordx4 v[30:31], v[24:27], off nt
	global_store_dwordx4 v[12:13], v[8:11], off nt
